# P2 conv tile pairs assigned so each XCD gets a contiguous range of pairs (overlapping input rows shared in its L2)
# speedup vs baseline: 1.0082x; 1.0004x over previous
; template <int TT>
; __device__ __forceinline__ void conv_pair(const Params& p, unsigned char* lds, bool sample, int tile) {
;     int tid = threadIdx.x; asm volatile("" : "+v"(tid));
;     const int half = tid >> 8, cp = tid & 255, lane = tid & 63, wq = (tid >> 6) & 3;
;     unsigned char* ws = p.ws; const bf16_t* U = (const bf16_t*)(ws + WS_U); bf16_t* CAT = (bf16_t*)(ws + WS_CAT);
;     const int sq = sample ? tile : tile >> 7, t0 = sample ? 0 : (tile & 127) * 16;
;     const int row0 = sample ? MP + sq * DS : sq * SEQ + t0;
;     float* zb = (float*)lds + (size_t)half * (TT * MIXB);
; __global__ void __launch_bounds__(512, 2) hymba_fwd(Params p) {
;     ...
;         for (int u = CONV_MOVED + bx; u < NB * (SEQ / 16) / 2; u += G) conv_pair<16>(p, lds, false, 2 * u + (threadIdx.x >> 8));
.Lp2_conv:
	s_cmpk_lt_i32 s2, 0x100
	s_cselect_b64 s[28:29], -1, 0
	s_cmpk_gt_i32 s2, 0xdf
	s_cbranch_scc1 .LBB0_400
	s_and_b32 s100, s2, 7
	s_mul_i32 s100, s100, 28
	s_lshr_b32 s101, s2, 3
	s_add_u32 s100, s100, s101
	v_lshl_add_u32 v0, s100, 1, v96
	v_add_u32_e32 v89, 0x240, v0
	v_lshlrev_b32_e32 v0, 4, v96
	v_lshl_add_u32 v0, s2, 5, v0
	s_add_i32 s1, s2, 0x120
	s_lshl_b32 s3, s66, 1
	v_add_u32_e32 v90, 0x2403, v0
	s_lshl_b32 s10, s66, 5
	v_mov_b32_e32 v17, 0
	v_mov_b32_e32 v91, 0x358637bd
	s_mov_b32 s11, 0x800000
	s_mov_b32 s12, 0x96f6000
	s_branch .LBB0_336
